# y stores sc1 instead of nt (on top of stack6)
# baseline (speedup 1.0000x reference)
.LBB0_530:
	v_lshl_add_u64 v[130:131], v[130:131], 2, s[10:11]
	global_load_dword v182, v[130:131], off sc1
	global_load_dword v183, v[130:131], off offset:64 sc1
	global_load_dword v184, v[130:131], off offset:128 sc1
	global_load_dword v185, v[130:131], off offset:192 sc1
	global_load_dword v186, v[130:131], off offset:512 sc1
	global_load_dword v187, v[130:131], off offset:576 sc1
	global_load_dword v188, v[130:131], off offset:640 sc1
	global_load_dword v189, v[130:131], off offset:704 sc1
	v_mov_b32_e32 v178, 0x3727c5ac
	v_lshl_add_u64 v[132:133], s[66:67], 0, v[132:133]
	v_lshlrev_b64 v[128:129], 2, v[128:129]
	v_lshl_add_u64 v[132:133], v[132:133], 0, v[128:129]
	v_lshl_add_u64 v[136:137], v[136:137], 2, s[10:11]
	s_waitcnt vmcnt(0)
	v_mov_b32_e32 v170, v182
	v_fmamk_f32 v170, v170, 0x3a800000, v178
	v_rsq_f32_e32 v170, v170
	s_nop 0
	v_pk_mul_f32 v[124:125], v[124:125], v[170:171] op_sel_hi:[1,0]
	v_pk_mul_f32 v[126:127], v[126:127], v[170:171] op_sel_hi:[1,0]
	v_pk_mul_f32 v[120:121], v[120:121], v[170:171] op_sel_hi:[1,0]
	v_pk_mul_f32 v[122:123], v[122:123], v[170:171] op_sel_hi:[1,0]
	v_pk_mul_f32 v[172:173], v[116:117], v[170:171] op_sel_hi:[1,0]
	v_pk_mul_f32 v[174:175], v[118:119], v[170:171] op_sel_hi:[1,0]
	v_pk_mul_f32 v[176:177], v[112:113], v[170:171] op_sel_hi:[1,0]
	v_pk_mul_f32 v[170:171], v[114:115], v[170:171] op_sel_hi:[1,0]
	v_pk_mul_f32 v[114:115], v[14:15], v[126:127]
	v_pk_mul_f32 v[112:113], v[12:13], v[124:125]
	v_pk_mul_f32 v[118:119], v[10:11], v[122:123]
	v_pk_mul_f32 v[116:117], v[8:9], v[120:121]
	v_pk_mul_f32 v[122:123], v[6:7], v[174:175]
	v_pk_mul_f32 v[120:121], v[4:5], v[172:173]
	v_pk_mul_f32 v[126:127], v[2:3], v[170:171]
	v_pk_mul_f32 v[124:125], v[0:1], v[176:177]
	global_store_dwordx4 v[132:133], v[112:115], off sc1
	global_store_dwordx4 v[132:133], v[116:119], off offset:64 sc1
	global_store_dwordx4 v[132:133], v[120:123], off offset:512 sc1
	global_store_dwordx4 v[132:133], v[124:127], off offset:576 sc1
	v_mov_b32_e32 v112, v183
	v_lshl_add_u64 v[114:115], s[66:67], 0, v[134:135]
	v_lshl_add_u64 v[114:115], v[114:115], 0, v[128:129]
	v_lshl_add_u64 v[116:117], v[140:141], 2, s[10:11]
	v_fmamk_f32 v112, v112, 0x3a800000, v178
	v_rsq_f32_e32 v112, v112
	s_nop 0
	v_pk_mul_f32 v[108:109], v[108:109], v[112:113] op_sel_hi:[1,0]
	v_pk_mul_f32 v[110:111], v[110:111], v[112:113] op_sel_hi:[1,0]
	v_pk_mul_f32 v[104:105], v[104:105], v[112:113] op_sel_hi:[1,0]
	v_pk_mul_f32 v[106:107], v[106:107], v[112:113] op_sel_hi:[1,0]
	v_pk_mul_f32 v[118:119], v[100:101], v[112:113] op_sel_hi:[1,0]
	v_pk_mul_f32 v[120:121], v[102:103], v[112:113] op_sel_hi:[1,0]
	v_pk_mul_f32 v[122:123], v[96:97], v[112:113] op_sel_hi:[1,0]
	v_pk_mul_f32 v[112:113], v[98:99], v[112:113] op_sel_hi:[1,0]
	v_pk_mul_f32 v[98:99], v[14:15], v[110:111]
	v_pk_mul_f32 v[96:97], v[12:13], v[108:109]
	v_pk_mul_f32 v[102:103], v[10:11], v[106:107]
	v_pk_mul_f32 v[100:101], v[8:9], v[104:105]
	v_pk_mul_f32 v[106:107], v[6:7], v[120:121]
	v_pk_mul_f32 v[104:105], v[4:5], v[118:119]
	v_pk_mul_f32 v[110:111], v[2:3], v[112:113]
	v_pk_mul_f32 v[108:109], v[0:1], v[122:123]
	global_store_dwordx4 v[114:115], v[96:99], off sc1
	global_store_dwordx4 v[114:115], v[100:103], off offset:64 sc1
	global_store_dwordx4 v[114:115], v[104:107], off offset:512 sc1
	global_store_dwordx4 v[114:115], v[108:111], off offset:576 sc1
	v_mov_b32_e32 v96, v184
	v_lshl_add_u64 v[98:99], s[66:67], 0, v[138:139]
	v_lshl_add_u64 v[98:99], v[98:99], 0, v[128:129]
	v_lshl_add_u64 v[100:101], v[144:145], 2, s[10:11]
	v_fmamk_f32 v96, v96, 0x3a800000, v178
	v_rsq_f32_e32 v96, v96
	s_nop 0
	v_pk_mul_f32 v[92:93], v[92:93], v[96:97] op_sel_hi:[1,0]
	v_pk_mul_f32 v[94:95], v[94:95], v[96:97] op_sel_hi:[1,0]
	v_pk_mul_f32 v[88:89], v[88:89], v[96:97] op_sel_hi:[1,0]
	v_pk_mul_f32 v[90:91], v[90:91], v[96:97] op_sel_hi:[1,0]
	v_pk_mul_f32 v[102:103], v[84:85], v[96:97] op_sel_hi:[1,0]
	v_pk_mul_f32 v[104:105], v[86:87], v[96:97] op_sel_hi:[1,0]
	v_pk_mul_f32 v[106:107], v[80:81], v[96:97] op_sel_hi:[1,0]
	v_pk_mul_f32 v[96:97], v[82:83], v[96:97] op_sel_hi:[1,0]
	v_pk_mul_f32 v[82:83], v[14:15], v[94:95]
	v_pk_mul_f32 v[80:81], v[12:13], v[92:93]
	v_pk_mul_f32 v[86:87], v[10:11], v[90:91]
	v_pk_mul_f32 v[84:85], v[8:9], v[88:89]
	v_pk_mul_f32 v[90:91], v[6:7], v[104:105]
	v_pk_mul_f32 v[88:89], v[4:5], v[102:103]
	v_pk_mul_f32 v[94:95], v[2:3], v[96:97]
	v_pk_mul_f32 v[92:93], v[0:1], v[106:107]
	global_store_dwordx4 v[98:99], v[80:83], off sc1
	global_store_dwordx4 v[98:99], v[84:87], off offset:64 sc1
	global_store_dwordx4 v[98:99], v[88:91], off offset:512 sc1
	global_store_dwordx4 v[98:99], v[92:95], off offset:576 sc1
	v_mov_b32_e32 v80, v185
	v_lshl_add_u64 v[82:83], s[66:67], 0, v[142:143]
	v_lshl_add_u64 v[82:83], v[82:83], 0, v[128:129]
	v_fmamk_f32 v80, v80, 0x3a800000, v178
	v_rsq_f32_e32 v80, v80
	s_nop 0
	v_pk_mul_f32 v[84:85], v[146:147], v[80:81] op_sel_hi:[1,0]
	v_pk_mul_f32 v[78:79], v[78:79], v[80:81] op_sel_hi:[1,0]
	v_pk_mul_f32 v[76:77], v[76:77], v[80:81] op_sel_hi:[1,0]
	v_pk_mul_f32 v[74:75], v[74:75], v[80:81] op_sel_hi:[1,0]
	v_pk_mul_f32 v[86:87], v[68:69], v[80:81] op_sel_hi:[1,0]
	v_pk_mul_f32 v[88:89], v[70:71], v[80:81] op_sel_hi:[1,0]
	v_pk_mul_f32 v[90:91], v[64:65], v[80:81] op_sel_hi:[1,0]
	v_pk_mul_f32 v[80:81], v[66:67], v[80:81] op_sel_hi:[1,0]
	v_pk_mul_f32 v[66:67], v[14:15], v[78:79]
	v_pk_mul_f32 v[64:65], v[12:13], v[84:85]
	v_pk_mul_f32 v[70:71], v[10:11], v[74:75]
	v_pk_mul_f32 v[68:69], v[8:9], v[76:77]
	v_pk_mul_f32 v[76:77], v[6:7], v[88:89]
	v_pk_mul_f32 v[74:75], v[4:5], v[86:87]
	v_pk_mul_f32 v[80:81], v[2:3], v[80:81]
	v_pk_mul_f32 v[78:79], v[0:1], v[90:91]
	global_store_dwordx4 v[82:83], v[64:67], off sc1
	global_store_dwordx4 v[82:83], v[68:71], off offset:64 sc1
	global_store_dwordx4 v[82:83], v[74:77], off offset:512 sc1
	global_store_dwordx4 v[82:83], v[78:81], off offset:576 sc1
	v_mov_b32_e32 v64, v186
	v_lshl_add_u64 v[66:67], s[66:67], 0, v[72:73]
	v_lshl_add_u64 v[66:67], v[66:67], 0, v[128:129]
	v_fmamk_f32 v64, v64, 0x3a800000, v178
	v_rsq_f32_e32 v64, v64
	s_nop 0
	v_pk_mul_f32 v[68:69], v[148:149], v[64:65] op_sel_hi:[1,0]
	v_pk_mul_f32 v[62:63], v[62:63], v[64:65] op_sel_hi:[1,0]
	v_pk_mul_f32 v[60:61], v[60:61], v[64:65] op_sel_hi:[1,0]
	v_pk_mul_f32 v[58:59], v[58:59], v[64:65] op_sel_hi:[1,0]
	v_pk_mul_f32 v[70:71], v[52:53], v[64:65] op_sel_hi:[1,0]
	v_pk_mul_f32 v[72:73], v[54:55], v[64:65] op_sel_hi:[1,0]
	v_pk_mul_f32 v[74:75], v[48:49], v[64:65] op_sel_hi:[1,0]
	v_pk_mul_f32 v[64:65], v[50:51], v[64:65] op_sel_hi:[1,0]
	v_pk_mul_f32 v[50:51], v[14:15], v[62:63]
	v_pk_mul_f32 v[48:49], v[12:13], v[68:69]
	v_pk_mul_f32 v[54:55], v[10:11], v[58:59]
	v_pk_mul_f32 v[52:53], v[8:9], v[60:61]
	v_pk_mul_f32 v[60:61], v[6:7], v[72:73]
	v_pk_mul_f32 v[58:59], v[4:5], v[70:71]
	v_pk_mul_f32 v[64:65], v[2:3], v[64:65]
	v_pk_mul_f32 v[62:63], v[0:1], v[74:75]
	global_store_dwordx4 v[66:67], v[48:51], off sc1
	global_store_dwordx4 v[66:67], v[52:55], off offset:64 sc1
	global_store_dwordx4 v[66:67], v[58:61], off offset:512 sc1
	global_store_dwordx4 v[66:67], v[62:65], off offset:576 sc1
	v_mov_b32_e32 v48, v187
	v_lshl_add_u64 v[50:51], s[66:67], 0, v[56:57]
	v_lshl_add_u64 v[50:51], v[50:51], 0, v[128:129]
	v_fmamk_f32 v48, v48, 0x3a800000, v178
	v_rsq_f32_e32 v48, v48
	s_nop 0
	v_pk_mul_f32 v[52:53], v[150:151], v[48:49] op_sel_hi:[1,0]
	v_pk_mul_f32 v[46:47], v[46:47], v[48:49] op_sel_hi:[1,0]
	v_pk_mul_f32 v[44:45], v[44:45], v[48:49] op_sel_hi:[1,0]
	v_pk_mul_f32 v[42:43], v[42:43], v[48:49] op_sel_hi:[1,0]
	v_pk_mul_f32 v[54:55], v[36:37], v[48:49] op_sel_hi:[1,0]
	v_pk_mul_f32 v[56:57], v[38:39], v[48:49] op_sel_hi:[1,0]
	v_pk_mul_f32 v[58:59], v[32:33], v[48:49] op_sel_hi:[1,0]
	v_pk_mul_f32 v[48:49], v[34:35], v[48:49] op_sel_hi:[1,0]
	v_pk_mul_f32 v[34:35], v[14:15], v[46:47]
	v_pk_mul_f32 v[32:33], v[12:13], v[52:53]
	v_pk_mul_f32 v[38:39], v[10:11], v[42:43]
	v_pk_mul_f32 v[36:37], v[8:9], v[44:45]
	v_pk_mul_f32 v[44:45], v[6:7], v[56:57]
	v_pk_mul_f32 v[42:43], v[4:5], v[54:55]
	v_pk_mul_f32 v[48:49], v[2:3], v[48:49]
	v_pk_mul_f32 v[46:47], v[0:1], v[58:59]
	global_store_dwordx4 v[50:51], v[32:35], off sc1
	global_store_dwordx4 v[50:51], v[36:39], off offset:64 sc1
	global_store_dwordx4 v[50:51], v[42:45], off offset:512 sc1
	global_store_dwordx4 v[50:51], v[46:49], off offset:576 sc1
	v_mov_b32_e32 v32, v188
	v_lshl_add_u64 v[34:35], s[66:67], 0, v[40:41]
	v_lshl_add_u64 v[34:35], v[34:35], 0, v[128:129]
	v_fmamk_f32 v32, v32, 0x3a800000, v178
	v_rsq_f32_e32 v32, v32
	s_nop 0
	v_pk_mul_f32 v[36:37], v[152:153], v[32:33] op_sel_hi:[1,0]
	v_pk_mul_f32 v[30:31], v[30:31], v[32:33] op_sel_hi:[1,0]
	v_pk_mul_f32 v[28:29], v[28:29], v[32:33] op_sel_hi:[1,0]
	v_pk_mul_f32 v[26:27], v[26:27], v[32:33] op_sel_hi:[1,0]
	v_pk_mul_f32 v[38:39], v[20:21], v[32:33] op_sel_hi:[1,0]
	v_pk_mul_f32 v[40:41], v[22:23], v[32:33] op_sel_hi:[1,0]
	v_pk_mul_f32 v[42:43], v[16:17], v[32:33] op_sel_hi:[1,0]
	v_pk_mul_f32 v[32:33], v[18:19], v[32:33] op_sel_hi:[1,0]
	v_pk_mul_f32 v[18:19], v[14:15], v[30:31]
	v_pk_mul_f32 v[16:17], v[12:13], v[36:37]
	v_pk_mul_f32 v[22:23], v[10:11], v[26:27]
	v_pk_mul_f32 v[20:21], v[8:9], v[28:29]
	v_pk_mul_f32 v[28:29], v[6:7], v[40:41]
	v_pk_mul_f32 v[26:27], v[4:5], v[38:39]
	v_pk_mul_f32 v[32:33], v[2:3], v[32:33]
	v_pk_mul_f32 v[30:31], v[0:1], v[42:43]
	global_store_dwordx4 v[34:35], v[16:19], off sc1
	global_store_dwordx4 v[34:35], v[20:23], off offset:64 sc1
	global_store_dwordx4 v[34:35], v[26:29], off offset:512 sc1
	global_store_dwordx4 v[34:35], v[30:33], off offset:576 sc1
	v_mov_b32_e32 v16, v189
	v_lshl_add_u64 v[18:19], s[66:67], 0, v[24:25]
	v_lshl_add_u64 v[18:19], v[18:19], 0, v[128:129]
	v_fmac_f32_e32 v178, 0x3a800000, v16
	v_rsq_f32_e32 v16, v178
	s_nop 0
	v_pk_mul_f32 v[20:21], v[168:169], v[16:17] op_sel_hi:[1,0]
	v_pk_mul_f32 v[22:23], v[166:167], v[16:17] op_sel_hi:[1,0]
	v_pk_mul_f32 v[24:25], v[164:165], v[16:17] op_sel_hi:[1,0]
	v_pk_mul_f32 v[26:27], v[162:163], v[16:17] op_sel_hi:[1,0]
	v_pk_mul_f32 v[28:29], v[160:161], v[16:17] op_sel_hi:[1,0]
	v_pk_mul_f32 v[30:31], v[158:159], v[16:17] op_sel_hi:[1,0]
	v_pk_mul_f32 v[32:33], v[156:157], v[16:17] op_sel_hi:[1,0]
	v_pk_mul_f32 v[16:17], v[154:155], v[16:17] op_sel_hi:[1,0]
	v_pk_mul_f32 v[14:15], v[14:15], v[22:23]
	v_pk_mul_f32 v[12:13], v[12:13], v[20:21]
	v_pk_mul_f32 v[10:11], v[10:11], v[26:27]
	v_pk_mul_f32 v[8:9], v[8:9], v[24:25]
	v_pk_mul_f32 v[6:7], v[6:7], v[30:31]
	v_pk_mul_f32 v[4:5], v[4:5], v[28:29]
	v_pk_mul_f32 v[2:3], v[2:3], v[16:17]
	v_pk_mul_f32 v[0:1], v[0:1], v[32:33]
	global_store_dwordx4 v[18:19], v[12:15], off sc1
	global_store_dwordx4 v[18:19], v[8:11], off offset:64 sc1
	global_store_dwordx4 v[18:19], v[4:7], off offset:512 sc1
	global_store_dwordx4 v[18:19], v[0:3], off offset:576 sc1
	s_bfe_u32 s0, s79, 0x20006
	s_cmp_lg_u32 s0, 0
	s_cbranch_scc1 .Ls3_done
	s_lshl_b32 s0, s72, 8
	s_add_u32 s0, s68, s0
	s_addc_u32 s1, s69, 0
	v_mov_b32_e32 v9, 0x48000
	s_mov_b32 s3, 0x100000
